# helper workgroups skip the next-layer weight packing; the other 216 two-m-tile workgroups cover it
# speedup vs baseline: 1.0071x; 1.0071x over previous
; DI int otid() { int t = threadIdx.x; asm volatile("" : "+v"(t)); return t; }
; DI void pack_layer(const Params& p, int l, int gtid_, int gthreads) {
;     int gtid = gtid_; asm volatile("" : "+v"(gtid));
;     bf16_t* w = (bf16_t*)(p.ws + OFF_WP) + (size_t)l * PW_LAYER;
;     pack_w(p.in[11] + (size_t)l * DM * DIN, p.in[10] + l * DM, DM, DIN, w + PW_IN, 1, gtid, gthreads);
; __global__ void __launch_bounds__(NTHR) mega(Params p) {
;     ...
;             if (G > 8) { if (tb >= 4) pack_layer(p, l + 1, (tb - 4) * NTHR + otid(), (G - 4) * NTHR); }
;             else pack_layer(p, l + 1, bid * NTHR + otid(), G * NTHR);
.LBB0_630:
	s_and_b64 vcc, exec, s[0:1]
	s_cbranch_vccz .LBB0_705
	v_readlane_b32 s0, v253, 49
	v_readlane_b32 s1, v253, 50
	s_andn2_b64 vcc, exec, s[0:1]
	s_cbranch_vccnz .LBB0_705
	v_readlane_b32 s0, v254, 57
	s_nop 3
	s_and_b32 s1, s0, 31
	s_cmp_lt_u32 s1, 5
	s_cbranch_scc1 .LBB0_705
	s_lshr_b32 s0, s0, 5
	s_mul_i32 s0, s0, 27
	s_add_u32 s0, s0, s1
	s_sub_u32 s0, s0, 5
	s_lshl_b32 s0, s0, 9
	s_mov_b32 s96, 0x1b000
	v_mov_b32_e32 v179, 0x6c000
	v_readlane_b32 s4, v252, 0
	v_mov_b32_e32 v0, v176
	s_mul_i32 s1, s90, 0x1f00000
	v_readlane_b32 s8, v252, 4
	v_readlane_b32 s9, v252, 5
	v_add_u32_e32 v41, s0, v0
	s_mul_hi_u32 s0, s90, 0x1f00000
	s_add_u32 s52, s8, s1
	s_addc_u32 s53, s9, s0
	s_mov_b32 s0, 0x22000
	s_movk_i32 s31, 0x3fff
	s_mov_b32 s91, s65
	s_lshl_b32 s64, s90, 10
	v_cmp_gt_i32_e32 vcc, s0, v41
	v_lshlrev_b32_e32 v43, 2, v41
	v_readlane_b32 s5, v252, 1
	v_readlane_b32 s6, v252, 2
	v_readlane_b32 s7, v252, 3
	v_readlane_b32 s10, v252, 6
	v_readlane_b32 s11, v252, 7
	s_and_saveexec_b64 s[2:3], vcc
	s_cbranch_execz .LBB0_651
	v_readlane_b32 s4, v252, 55
	s_mul_i32 s1, s90, 0x1100000
	v_readlane_b32 s10, v252, 61
	s_mul_hi_u32 s0, s90, 0x1100000
	v_readlane_b32 s5, v252, 56
	v_readlane_b32 s11, v252, 62
	s_add_u32 s4, s10, s1
	v_readlane_b32 s6, v252, 57
	v_readlane_b32 s8, v252, 59
	s_addc_u32 s5, s11, s0
	s_lshl_b64 s[0:1], s[64:65], 2
	v_readlane_b32 s7, v252, 58
	v_readlane_b32 s9, v252, 60
	s_add_u32 s6, s8, s0
	s_addc_u32 s7, s9, s1
	v_lshlrev_b32_e32 v0, 2, v41
	s_mov_b64 s[10:11], 0
	v_mov_b32_e32 v40, v41
	v_readlane_b32 s12, v252, 63
	v_readlane_b32 s13, v253, 0
	v_readlane_b32 s14, v253, 1
	v_readlane_b32 s15, v253, 2
	v_readlane_b32 s16, v253, 3
	v_readlane_b32 s17, v253, 4
	v_readlane_b32 s18, v253, 5
	v_readlane_b32 s19, v253, 6
	s_branch .LBB0_635

; __device__ __forceinline__ unsigned xb_add(unsigned* p, unsigned v) { return __hip_atomic_fetch_add(p, v, __ATOMIC_RELAXED, __HIP_MEMORY_SCOPE_AGENT); }
; __device__ __forceinline__ void xcd_barrier(const XcdBarrier& b) {
;     asm volatile("s_waitcnt vmcnt(0)" ::: "memory");
;     __syncthreads();
;     if (threadIdx.x == 0) {
;         unsigned* bar = b.bar;
;         __builtin_amdgcn_s_waitcnt(0);
;         unsigned nloc = b.st[0], nx = b.st[1];
;         if (nloc == 0u) { xcd_barrier_complete(bar, b.x, nloc, nx); b.st[0] = nloc; b.st[1] = nx; }
;         const unsigned old = xb_add(&bar[XB_XSUB(b.x)], 1u);
.Lhu_done:
	s_add_i32 s96, s92, 0xfffff800
	v_add_u32_e32 v179, 0xffffe000, v177
	s_getreg_b32 s2, hwreg(HW_REG_XCC_ID, 0, 4)
	s_waitcnt vmcnt(0)
	s_waitcnt lgkmcnt(0)
	s_barrier
	s_mov_b64 s[0:1], exec
	v_readlane_b32 s4, v252, 8
	v_readlane_b32 s5, v252, 9
	s_and_b64 s[4:5], s[0:1], s[4:5]
	s_mov_b64 exec, s[4:5]
	s_cbranch_execz .LBB0_757
	v_mov_b32_e32 v0, 0x20400
	s_waitcnt vmcnt(0) expcnt(0) lgkmcnt(0)
	ds_read_b32 v3, v0
	v_mov_b32_e32 v0, 0x20404
	ds_read_b32 v2, v0
	s_and_b32 s8, s2, 15
	s_waitcnt lgkmcnt(1)
	v_cmp_ne_u32_e32 vcc, 0, v3
	s_cbranch_vccnz .LBB0_721
	s_mov_b32 s9, 1
	s_branch .LBB0_709
